# added: prologue gain factors via scalar loads (item prefetch stays in flight) + single-counter grid sync replacing the cooperative-groups sync
# speedup vs baseline: 1.0095x; 1.0095x over previous
.LBB0_180:
	v_lshrrev_b32_e32 v1, 20, v0
	v_lshrrev_b32_e32 v0, 10, v0
	s_waitcnt lgkmcnt(0)
	s_barrier
	s_waitcnt vmcnt(0) lgkmcnt(0)
	v_or_b32_e32 v0, v0, v1
	s_movk_i32 s0, 0x3ff
	v_and_or_b32 v0, v0, s0, v195
	v_cmp_eq_u32_e32 vcc, 0, v0
	s_barrier
	s_and_saveexec_b64 s[0:1], vcc
	v_readlane_b32 s72, v252, 2
	v_readlane_b32 s73, v252, 3
	s_cbranch_execz .LBB0_190
	buffer_wbl2 sc1
	s_waitcnt vmcnt(0)
	v_readlane_b32 s4, v252, 0
	v_readlane_b32 s5, v252, 1
	s_add_u32 s4, s4, 0x36b0
	s_addc_u32 s5, s5, 0
	v_mov_b32_e32 v2, 0
	v_mov_b32_e32 v3, 1
	s_nop 4
	global_atomic_add v2, v3, s[4:5]
.Lgsync_spin:
	global_load_dword v3, v2, s[4:5] sc1
	s_waitcnt vmcnt(0)
	v_cmp_ne_u32_e32 vcc, s94, v3
	s_cbranch_vccz .Lgsync_done
	s_sleep 1
	s_branch .Lgsync_spin
